# diff-attn unit prologue: Q-image copy de-serialised (8 loads issued together, counted vmcnt)
# baseline (speedup 1.0000x reference)
.LBB0_429:
	s_ashr_i32 s2, s33, 8
	v_readfirstlane_b32 s5, v1
	s_ashr_i32 s3, s2, 31
	s_lshr_b32 s4, s5, 6
	s_lshl_b64 s[6:7], s[2:3], 13
	s_lshl_b32 s3, s33, 8
	s_and_b32 s3, s3, 0x1f00
	s_lshl_b32 s8, s4, 5
	s_add_i32 s8, s8, s3
	s_add_u32 s6, s6, s8
	s_addc_u32 s7, s7, 0
	s_mulk_i32 s7, 0x2a00
	s_mul_hi_u32 s8, s6, 0x2a00
	s_add_i32 s8, s8, s7
	s_mulk_i32 s6, 0x2a00
	s_add_u32 s6, s14, s6
	s_addc_u32 s7, s15, s8
	s_lshl_b32 s8, s33, 2
	v_mov_b32_e32 v223, v219
	s_and_b32 s8, s8, 0x380
	v_mov_b32_e32 v2, v219
	s_lshl_b32 s9, s8, 1
	s_add_u32 s40, s6, s9
	v_ashrrev_i32_e32 v4, 4, v2
	v_mul_lo_u32 v5, v4, s48
	v_and_b32_e32 v6, 15, v2
	s_mul_i32 s3, s4, 0x2200
	s_addc_u32 s41, s7, 0
	v_lshl_or_b32 v2, v6, 3, v5
	v_mul_lo_u32 v7, v4, s49
	v_lshlrev_b32_e32 v6, 4, v6
	v_lshl_add_u64 v[4:5], v[2:3], 1, s[40:41]
	v_add_u32_e32 v2, s3, v7
	v_add3_u32 v2, v2, v6, s50
	global_load_dwordx4 v[18:21], v[4:5], off
	v_lshl_add_u64 v[6:7], v[4:5], 0, s[18:19]
	global_load_dwordx4 v[22:25], v[6:7], off
	v_lshl_add_u64 v[6:7], v[6:7], 0, s[18:19]
	global_load_dwordx4 v[26:29], v[6:7], off
	v_lshl_add_u64 v[6:7], v[6:7], 0, s[18:19]
	global_load_dwordx4 v[30:33], v[6:7], off
	v_lshl_add_u64 v[6:7], v[6:7], 0, s[18:19]
	global_load_dwordx4 v[34:37], v[6:7], off
	v_lshl_add_u64 v[6:7], v[6:7], 0, s[18:19]
	global_load_dwordx4 v[38:41], v[6:7], off
	v_lshl_add_u64 v[6:7], v[6:7], 0, s[18:19]
	global_load_dwordx4 v[42:45], v[6:7], off
	v_lshl_add_u64 v[6:7], v[6:7], 0, s[18:19]
	global_load_dwordx4 v[46:49], v[6:7], off
	s_waitcnt vmcnt(7)
	ds_write_b128 v2, v[18:21]
	s_waitcnt vmcnt(6)
	ds_write_b128 v2, v[22:25] offset:1088
	s_waitcnt vmcnt(5)
	ds_write_b128 v2, v[26:29] offset:2176
	s_waitcnt vmcnt(4)
	ds_write_b128 v2, v[30:33] offset:3264
	s_waitcnt vmcnt(3)
	ds_write_b128 v2, v[34:37] offset:4352
	s_waitcnt vmcnt(2)
	ds_write_b128 v2, v[38:41] offset:5440
	s_waitcnt vmcnt(1)
	ds_write_b128 v2, v[42:45] offset:6528
	s_waitcnt vmcnt(0)
	ds_write_b128 v2, v[46:49] offset:7616
	v_ashrrev_i32_e32 v4, 3, v223
	v_lshl_add_u32 v2, s4, 3, v4
	v_lshrrev_b32_e32 v5, 1, v2
	v_xor_b32_e32 v5, v5, v223
	s_mul_i32 s7, s2, 0x5400000
	v_lshlrev_b32_e32 v5, 3, v5
	s_mul_hi_i32 s6, s2, 0x5400000
	s_add_u32 s2, s14, s7
	v_and_b32_e32 v7, 56, v5
	v_ashrrev_i32_e32 v5, 4, v223
	s_addc_u32 s9, s15, s6
	s_lshl_b32 s8, s8, 1
	v_lshl_add_u32 v6, s4, 2, v5
	v_mul_lo_u32 v8, v6, s48
	v_and_b32_e32 v6, 15, v223
	v_lshlrev_b32_e32 v9, 2, v5
	v_mul_lo_u32 v2, v2, s48
	s_add_u32 s8, s2, s8
	v_bitop3_b32 v6, v9, v6, 12 bitop3:0x6c
	v_or_b32_e32 v2, v7, v2
	s_addc_u32 s9, s9, 0
	s_lshl_b32 s2, s4, 10
	v_lshlrev_b32_e32 v6, 3, v6
	v_lshl_add_u64 v[10:11], v[2:3], 1, s[8:9]
	s_add_i32 s55, s2, 0
	v_or_b32_e32 v8, v8, v6
	v_mov_b32_e32 v224, 0
	v_lshl_add_u64 v[12:13], v[10:11], 0, s[22:23]
	s_mov_b32 m0, s55
	v_mov_b32_e32 v9, v3
	global_load_lds_dwordx4 v[12:13], off
	v_lshl_add_u64 v[10:11], v[10:11], 0, s[24:25]
	s_add_i32 m0, s55, 0x2000
	v_lshl_add_u64 v[8:9], v[8:9], 1, s[8:9]
	global_load_lds_dwordx4 v[10:11], off
	v_lshl_add_u64 v[10:11], v[8:9], 0, s[26:27]
	s_add_i32 m0, s55, 0x4000
	v_lshl_add_u64 v[8:9], v[8:9], 0, s[28:29]
	global_load_lds_dwordx4 v[10:11], off
	s_add_i32 m0, s55, 0x6000
	s_cmpk_lt_u32 s5, 0x100
	global_load_lds_dwordx4 v[8:9], off
	s_cbranch_scc0 .LBB0_433
	s_setprio 1
